# attention PV blocks: 4-deep LDS fragment prefetch instead of read-wait-mfma
# speedup vs baseline: 1.0145x; 1.0015x over previous
.LBB0_1354:
	s_and_saveexec_b64 s[44:45], s[38:39]
	s_cbranch_execz .LBB0_1356
	s_setprio 1
	v_mad_u64_u32 v[172:173], s[48:49], v232, s93, v[168:169]
	v_add_u32_e32 v173, 0x4000, v172
	ds_read2_b64 v[128:131], v173 offset1:4
	ds_read2_b64 v[132:135], v173 offset0:8 offset1:12
	v_add_u32_e32 v173, 0x4800, v172
	ds_read2_b64 v[136:139], v173 offset0:16 offset1:20
	ds_read2_b64 v[140:143], v173 offset0:24 offset1:28
	s_waitcnt lgkmcnt(3)
	v_mfma_f32_16x16x32_bf16 v[92:95], v[128:131], v[112:115], v[92:95]
	v_mfma_f32_16x16x32_bf16 v[60:63], v[128:131], v[120:123], v[60:63]
	v_add_u32_e32 v173, 0x5000, v172
	ds_read2_b64 v[128:131], v173 offset0:32 offset1:36
	s_waitcnt lgkmcnt(3)
	v_mfma_f32_16x16x32_bf16 v[92:95], v[132:135], v[116:119], v[92:95]
	v_mfma_f32_16x16x32_bf16 v[60:63], v[132:135], v[124:127], v[60:63]
	ds_read2_b64 v[132:135], v173 offset0:40 offset1:44
	s_waitcnt lgkmcnt(3)
	v_mfma_f32_16x16x32_bf16 v[88:91], v[136:139], v[112:115], v[88:91]
	v_mfma_f32_16x16x32_bf16 v[56:59], v[136:139], v[120:123], v[56:59]
	v_add_u32_e32 v173, 0x5800, v172
	ds_read2_b64 v[136:139], v173 offset0:48 offset1:52
	s_waitcnt lgkmcnt(3)
	v_mfma_f32_16x16x32_bf16 v[88:91], v[140:143], v[116:119], v[88:91]
	v_mfma_f32_16x16x32_bf16 v[56:59], v[140:143], v[124:127], v[56:59]
	ds_read2_b64 v[140:143], v173 offset0:56 offset1:60
	s_waitcnt lgkmcnt(3)
	v_mfma_f32_16x16x32_bf16 v[84:87], v[128:131], v[112:115], v[84:87]
	v_mfma_f32_16x16x32_bf16 v[52:55], v[128:131], v[120:123], v[52:55]
	v_add_u32_e32 v173, 0x6000, v172
	ds_read2_b64 v[128:131], v173 offset0:64 offset1:68
	s_waitcnt lgkmcnt(3)
	v_mfma_f32_16x16x32_bf16 v[84:87], v[132:135], v[116:119], v[84:87]
	v_mfma_f32_16x16x32_bf16 v[52:55], v[132:135], v[124:127], v[52:55]
	ds_read2_b64 v[132:135], v173 offset0:72 offset1:76
	s_waitcnt lgkmcnt(3)
	v_mfma_f32_16x16x32_bf16 v[80:83], v[136:139], v[112:115], v[80:83]
	v_mfma_f32_16x16x32_bf16 v[48:51], v[136:139], v[120:123], v[48:51]
	v_add_u32_e32 v173, 0x6800, v172
	ds_read2_b64 v[136:139], v173 offset0:80 offset1:84
	s_waitcnt lgkmcnt(3)
	v_mfma_f32_16x16x32_bf16 v[80:83], v[140:143], v[116:119], v[80:83]
	v_mfma_f32_16x16x32_bf16 v[48:51], v[140:143], v[124:127], v[48:51]
	ds_read2_b64 v[140:143], v173 offset0:88 offset1:92
	s_waitcnt lgkmcnt(3)
	v_mfma_f32_16x16x32_bf16 v[76:79], v[128:131], v[112:115], v[76:79]
	v_mfma_f32_16x16x32_bf16 v[44:47], v[128:131], v[120:123], v[44:47]
	v_add_u32_e32 v173, 0x7000, v172
	ds_read2_b64 v[128:131], v173 offset0:96 offset1:100
	s_waitcnt lgkmcnt(3)
	v_mfma_f32_16x16x32_bf16 v[76:79], v[132:135], v[116:119], v[76:79]
	v_mfma_f32_16x16x32_bf16 v[44:47], v[132:135], v[124:127], v[44:47]
	ds_read2_b64 v[132:135], v173 offset0:104 offset1:108
	s_waitcnt lgkmcnt(3)
	v_mfma_f32_16x16x32_bf16 v[72:75], v[136:139], v[112:115], v[72:75]
	v_mfma_f32_16x16x32_bf16 v[40:43], v[136:139], v[120:123], v[40:43]
	v_add_u32_e32 v173, 0x7800, v172
	ds_read2_b64 v[136:139], v173 offset0:112 offset1:116
	s_waitcnt lgkmcnt(3)
	v_mfma_f32_16x16x32_bf16 v[72:75], v[140:143], v[116:119], v[72:75]
	v_mfma_f32_16x16x32_bf16 v[40:43], v[140:143], v[124:127], v[40:43]
	ds_read2_b64 v[140:143], v173 offset0:120 offset1:124
	s_waitcnt lgkmcnt(3)
	v_mfma_f32_16x16x32_bf16 v[68:71], v[128:131], v[112:115], v[68:71]
	v_mfma_f32_16x16x32_bf16 v[36:39], v[128:131], v[120:123], v[36:39]
	s_waitcnt lgkmcnt(2)
	v_mfma_f32_16x16x32_bf16 v[68:71], v[132:135], v[116:119], v[68:71]
	v_mfma_f32_16x16x32_bf16 v[36:39], v[132:135], v[124:127], v[36:39]
	s_waitcnt lgkmcnt(1)
	v_mfma_f32_16x16x32_bf16 v[64:67], v[136:139], v[112:115], v[64:67]
	v_mfma_f32_16x16x32_bf16 v[32:35], v[136:139], v[120:123], v[32:35]
	s_waitcnt lgkmcnt(0)
	v_mfma_f32_16x16x32_bf16 v[64:67], v[140:143], v[116:119], v[64:67]
	v_mfma_f32_16x16x32_bf16 v[32:35], v[140:143], v[124:127], v[32:35]
	s_setprio 0

; __device__ __forceinline__ unsigned pk2(float lo, float hi) { f32x2 v = {lo, hi}; bf16x2_t b = __builtin_convertvector(v, bf16x2_t); return __builtin_bit_cast(unsigned, b); }
; __device__ __forceinline__ void attn_phase(LAS unsigned char* lds, const bf16_t* QKV, const float* kmean, const float* biasT, bf16_t* O, int G, int wg) {
;     ...
;                 for (int st = 0; st < 4; ++st)
; #pragma unroll
;                     for (int j = 0; j < 4; ++j) { const float p = __builtin_amdgcn_exp2f(sc[z][st][j] - m_sub); sc[z][st][j] = p; ps += p; }
;                 l_run[z] = l_run[z] * alpha + ps;
;                 if (__builtin_amdgcn_ballot_w64(alpha != 1.0f) != 0ull) {
; #pragma unroll
;                     for (int e = 0; e < 8; ++e) oacc[z][e] = oacc[z][e] * alpha;
;                 }
; #pragma unroll
;                 for (int i = 0; i < 2; ++i) { u32x4 w; w.x = pk2(sc[z][2 * i][0], sc[z][2 * i][1]); w.y = pk2(sc[z][2 * i][2], sc[z][2 * i][3]); w.z = pk2(sc[z][2 * i + 1][0], sc[z][2 * i + 1][1]); w.w = pk2(sc[z][2 * i + 1][2], sc[z][2 * i + 1][3]); pf[z][i] = __builtin_bit_cast(bf16x8, w); }
;             }
;             if (skew) { pend = true; pend_buf = cur_; } else ATT_PV(sb);
.LBB0_1369:
	v_cndmask_b32_e64 v112, v216, v139, s[44:45]
	v_sub_f32_e32 v113, v130, v112
	v_exp_f32_e32 v130, v113
	v_sub_f32_e32 v113, v131, v112
	v_exp_f32_e32 v131, v113
	v_sub_f32_e32 v113, v132, v112
	v_exp_f32_e32 v132, v113
	v_sub_f32_e32 v113, v133, v112
	v_exp_f32_e32 v133, v113
	v_sub_f32_e32 v113, v134, v112
	v_exp_f32_e32 v134, v113
	v_sub_f32_e32 v113, v135, v112
	v_exp_f32_e32 v135, v113
	v_sub_f32_e32 v113, v136, v112
	v_exp_f32_e32 v136, v113
	v_sub_f32_e32 v113, v137, v112
	v_exp_f32_e32 v137, v113
	v_sub_f32_e32 v113, v140, v112
	v_exp_f32_e32 v140, v113
	v_sub_f32_e32 v113, v141, v112
	v_exp_f32_e32 v141, v113
	v_sub_f32_e32 v113, v142, v112
	v_exp_f32_e32 v142, v113
	v_sub_f32_e32 v113, v143, v112
	v_exp_f32_e32 v143, v113
	v_sub_f32_e32 v113, v202, v112
	v_exp_f32_e32 v172, v113
	v_sub_f32_e32 v113, v203, v112
	v_exp_f32_e32 v173, v113
	v_sub_f32_e32 v113, v204, v112
	v_sub_f32_e32 v112, v205, v112
	v_exp_f32_e32 v203, v112
	v_cndmask_b32_e64 v112, v216, v129, s[0:1]
	v_exp_f32_e32 v202, v113
	v_sub_f32_e32 v113, v186, v112
	v_exp_f32_e32 v186, v113
	v_sub_f32_e32 v113, v187, v112
	v_exp_f32_e32 v187, v113
	v_sub_f32_e32 v113, v188, v112
	v_exp_f32_e32 v188, v113
	v_sub_f32_e32 v113, v189, v112
	v_exp_f32_e32 v189, v113
	v_sub_f32_e32 v113, v190, v112
	v_exp_f32_e32 v190, v113
	v_sub_f32_e32 v113, v191, v112
	v_exp_f32_e32 v191, v113
	v_sub_f32_e32 v113, v192, v112
	v_exp_f32_e32 v192, v113
	v_sub_f32_e32 v113, v193, v112
	v_exp_f32_e32 v193, v113
	v_sub_f32_e32 v113, v194, v112
	v_exp_f32_e32 v194, v113
	v_sub_f32_e32 v113, v195, v112
	v_exp_f32_e32 v195, v113
	v_sub_f32_e32 v113, v196, v112
	v_exp_f32_e32 v196, v113
	v_sub_f32_e32 v113, v197, v112
	v_exp_f32_e32 v197, v113
	v_sub_f32_e32 v113, v198, v112
	v_exp_f32_e32 v198, v113
	v_sub_f32_e32 v113, v199, v112
	v_exp_f32_e32 v199, v113
	v_sub_f32_e32 v113, v200, v112
	v_sub_f32_e32 v112, v201, v112
	v_exp_f32_e32 v200, v113
	v_exp_f32_e32 v201, v112
	v_cvt_pk_bf16_f32 v112, v186, v187
	v_cvt_pk_bf16_f32 v113, v188, v189
	v_cvt_pk_bf16_f32 v114, v190, v191
	v_cvt_pk_bf16_f32 v115, v192, v193
	v_cvt_pk_bf16_f32 v116, v194, v195
	v_cvt_pk_bf16_f32 v117, v196, v197
	v_cvt_pk_bf16_f32 v118, v198, v199
	v_cvt_pk_bf16_f32 v119, v200, v201
	v_cvt_pk_bf16_f32 v120, v130, v131
	v_cvt_pk_bf16_f32 v121, v132, v133
	v_cvt_pk_bf16_f32 v122, v134, v135
	v_cvt_pk_bf16_f32 v123, v136, v137
	v_cvt_pk_bf16_f32 v124, v140, v141
	v_cvt_pk_bf16_f32 v125, v142, v143
	v_cvt_pk_bf16_f32 v126, v172, v173
	v_cvt_pk_bf16_f32 v127, v202, v203
	s_mov_b64 s[44:45], -1
	v_mov_b32_e32 v204, s59
	s_and_saveexec_b64 s[0:1], s[40:41]
	s_cbranch_execz .LBB0_1371
	s_setprio 1
	v_add3_u32 v204, s60, v207, v223
	v_add_u32_e32 v205, 0x4000, v204
	ds_read2_b64 v[176:179], v205 offset1:4
	ds_read2_b64 v[234:237], v205 offset0:8 offset1:12
	v_add_u32_e32 v205, 0x4800, v204
	ds_read2_b64 v[238:241], v205 offset0:16 offset1:20
	ds_read2_b64 v[242:245], v205 offset0:24 offset1:28
	s_waitcnt lgkmcnt(3)
	v_mfma_f32_16x16x32_bf16 v[92:95], v[176:179], v[112:115], v[92:95]
	v_mfma_f32_16x16x32_bf16 v[60:63], v[176:179], v[120:123], v[60:63]
	v_add_u32_e32 v205, 0x5000, v204
	ds_read2_b64 v[176:179], v205 offset0:32 offset1:36
	s_waitcnt lgkmcnt(3)
	v_mfma_f32_16x16x32_bf16 v[92:95], v[234:237], v[116:119], v[92:95]
	v_mfma_f32_16x16x32_bf16 v[60:63], v[234:237], v[124:127], v[60:63]
	ds_read2_b64 v[234:237], v205 offset0:40 offset1:44
	s_waitcnt lgkmcnt(3)
	v_mfma_f32_16x16x32_bf16 v[88:91], v[238:241], v[112:115], v[88:91]
	v_mfma_f32_16x16x32_bf16 v[56:59], v[238:241], v[120:123], v[56:59]
	v_add_u32_e32 v205, 0x5800, v204
	ds_read2_b64 v[238:241], v205 offset0:48 offset1:52
	s_waitcnt lgkmcnt(3)
	v_mfma_f32_16x16x32_bf16 v[88:91], v[242:245], v[116:119], v[88:91]
	v_mfma_f32_16x16x32_bf16 v[56:59], v[242:245], v[124:127], v[56:59]
	ds_read2_b64 v[242:245], v205 offset0:56 offset1:60
	s_waitcnt lgkmcnt(3)
	v_mfma_f32_16x16x32_bf16 v[84:87], v[176:179], v[112:115], v[84:87]
	v_mfma_f32_16x16x32_bf16 v[52:55], v[176:179], v[120:123], v[52:55]
	v_add_u32_e32 v205, 0x6000, v204
	ds_read2_b64 v[176:179], v205 offset0:64 offset1:68
	s_waitcnt lgkmcnt(3)
	v_mfma_f32_16x16x32_bf16 v[84:87], v[234:237], v[116:119], v[84:87]
	v_mfma_f32_16x16x32_bf16 v[52:55], v[234:237], v[124:127], v[52:55]
	ds_read2_b64 v[234:237], v205 offset0:72 offset1:76
	s_waitcnt lgkmcnt(3)
	v_mfma_f32_16x16x32_bf16 v[80:83], v[238:241], v[112:115], v[80:83]
	v_mfma_f32_16x16x32_bf16 v[48:51], v[238:241], v[120:123], v[48:51]
	v_add_u32_e32 v205, 0x6800, v204
	ds_read2_b64 v[238:241], v205 offset0:80 offset1:84
	s_waitcnt lgkmcnt(3)
	v_mfma_f32_16x16x32_bf16 v[80:83], v[242:245], v[116:119], v[80:83]
	v_mfma_f32_16x16x32_bf16 v[48:51], v[242:245], v[124:127], v[48:51]
	ds_read2_b64 v[242:245], v205 offset0:88 offset1:92
	s_waitcnt lgkmcnt(3)
	v_mfma_f32_16x16x32_bf16 v[76:79], v[176:179], v[112:115], v[76:79]
	v_mfma_f32_16x16x32_bf16 v[44:47], v[176:179], v[120:123], v[44:47]
	v_add_u32_e32 v205, 0x7000, v204
	ds_read2_b64 v[176:179], v205 offset0:96 offset1:100
	s_waitcnt lgkmcnt(3)
	v_mfma_f32_16x16x32_bf16 v[76:79], v[234:237], v[116:119], v[76:79]
	v_mfma_f32_16x16x32_bf16 v[44:47], v[234:237], v[124:127], v[44:47]
	ds_read2_b64 v[234:237], v205 offset0:104 offset1:108
	s_waitcnt lgkmcnt(3)
	v_mfma_f32_16x16x32_bf16 v[72:75], v[238:241], v[112:115], v[72:75]
	v_mfma_f32_16x16x32_bf16 v[40:43], v[238:241], v[120:123], v[40:43]
	v_add_u32_e32 v205, 0x7800, v204
	ds_read2_b64 v[238:241], v205 offset0:112 offset1:116
	s_waitcnt lgkmcnt(3)
	v_mfma_f32_16x16x32_bf16 v[72:75], v[242:245], v[116:119], v[72:75]
	v_mfma_f32_16x16x32_bf16 v[40:43], v[242:245], v[124:127], v[40:43]
	ds_read2_b64 v[242:245], v205 offset0:120 offset1:124
	s_waitcnt lgkmcnt(3)
	v_mfma_f32_16x16x32_bf16 v[68:71], v[176:179], v[112:115], v[68:71]
	v_mfma_f32_16x16x32_bf16 v[36:39], v[176:179], v[120:123], v[36:39]
	s_waitcnt lgkmcnt(2)
	v_mfma_f32_16x16x32_bf16 v[68:71], v[234:237], v[116:119], v[68:71]
	v_mfma_f32_16x16x32_bf16 v[36:39], v[234:237], v[124:127], v[36:39]
	s_waitcnt lgkmcnt(1)
	v_mfma_f32_16x16x32_bf16 v[64:67], v[238:241], v[112:115], v[64:67]
	v_mfma_f32_16x16x32_bf16 v[32:35], v[238:241], v[120:123], v[32:35]
	s_waitcnt lgkmcnt(0)
	v_mfma_f32_16x16x32_bf16 v[64:67], v[242:245], v[116:119], v[64:67]
	v_mfma_f32_16x16x32_bf16 v[32:35], v[242:245], v[124:127], v[32:35]
	s_setprio 0
	s_xor_b64 s[44:45], exec, -1
	v_mov_b32_e32 v204, v232
